# phase F segment ends: all four gate tiles requested together before the MFMAs of the step (counted waits), instead of two early and two on demand
# speedup vs baseline: 1.0019x; 1.0019x over previous
; #define FG_BAR() do { asm volatile("s_waitcnt lgkmcnt(0)" ::: "memory"); __builtin_amdgcn_s_barrier(); asm volatile("" ::: "memory"); } while (0)
; __device__ __forceinline__ void branch_tile(LAS unsigned char* lds, const bf16_t* omix, const bf16_t* wbr, const bf16_t* brg, bf16_t* mix, int pm, int pn, int tid) {
;     ...
;     for (int kt = 0; kt < 16; kt += 2) {
;         fg_ld(A, Bt, (kt + 2 < 16 ? kt + 2 : 15), tid, ra0, rb0);
;         FG_COMPUTE(0);
;         fg_st(lds + FG_STAGE, tid, ra1, rb1);
;         FG_BAR();
;         fg_ld(A, Bt, (kt + 3 < 16 ? kt + 3 : 15), tid, ra1, rb1);
;         const bool segend = (kt == 2) || (kt == 6) || (kt == 14);
;         const int s = kt == 2 ? 0 : (kt == 6 ? 1 : 2);
;         u32x4 g0, g1;
;     ...
;         if (segend) { FG_GLD(g0, 0, 0); FG_GLD(g1, 0, 1); }
.LBB0_1092:
	s_mov_b32 s4, s27
	s_add_i32 s27, s27, 2
	s_cmp_gt_u32 s27, 13
	s_cselect_b64 s[14:15], -1, 0
	s_cmp_lt_u32 s27, 14
	s_cselect_b32 s76, s26, 0x3c0
	s_lshl_b64 s[28:29], s[76:77], 1
	s_add_u32 s30, s10, s28
	s_addc_u32 s31, s11, s29
	s_add_u32 s28, s12, s28
	s_addc_u32 s29, s13, s29
	v_lshl_add_u64 v[98:99], s[30:31], 0, v[130:131]
	v_lshl_add_u64 v[102:103], s[30:31], 0, v[132:133]
	v_lshl_add_u64 v[106:107], s[30:31], 0, v[134:135]
	v_lshl_add_u64 v[110:111], s[30:31], 0, v[136:137]
	v_lshl_add_u64 v[114:115], s[28:29], 0, v[130:131]
	v_lshl_add_u64 v[118:119], s[28:29], 0, v[132:133]
	global_load_dwordx4 v[98:101], v[98:99], off
	s_min_u32 s5, s27, 12
	global_load_dwordx4 v[102:105], v[102:103], off
	s_lshl_b32 s5, s5, 7
	global_load_dwordx4 v[106:109], v[106:107], off
	s_add_u32 s28, s10, s5
	global_load_dwordx4 v[110:113], v[110:111], off
	s_addc_u32 s29, s11, 0
	global_load_dwordx4 v[114:117], v[114:115], off
	s_nop 0
	global_load_dwordx4 v[118:121], v[118:119], off
	ds_read_b128 v[122:125], v242 offset:4608
	ds_read_b128 v[126:129], v238 offset:41472
	ds_read_b128 v[170:173], v242
	ds_read_b128 v[174:177], v242 offset:32
	ds_read_b128 v[244:247], v238 offset:36864
	ds_read_b128 v[248:251], v238 offset:36896
	s_waitcnt lgkmcnt(1)
	v_mfma_f32_32x32x16_bf16 v[48:63], v[170:173], v[244:247], v[48:63]
	v_mfma_f32_32x32x16_bf16 v[32:47], v[170:173], v[126:129], v[32:47]
	v_mfma_f32_32x32x16_bf16 v[16:31], v[122:125], v[244:247], v[16:31]
	v_mfma_f32_32x32x16_bf16 v[0:15], v[122:125], v[126:129], v[0:15]
	ds_read_b128 v[122:125], v242 offset:4640
	ds_read_b128 v[126:129], v238 offset:41504
	s_waitcnt lgkmcnt(2)
	v_mfma_f32_32x32x16_bf16 v[48:63], v[174:177], v[248:251], v[48:63]
	s_waitcnt lgkmcnt(0)
	v_mfma_f32_32x32x16_bf16 v[32:47], v[174:177], v[126:129], v[32:47]
	v_mfma_f32_32x32x16_bf16 v[16:31], v[122:125], v[248:251], v[16:31]
	v_mfma_f32_32x32x16_bf16 v[0:15], v[122:125], v[126:129], v[0:15]
	ds_read_b128 v[122:125], v242 offset:64
	ds_read_b128 v[126:129], v242 offset:4672
	ds_read_b128 v[170:173], v238 offset:36928
	ds_read_b128 v[174:177], v238 offset:41536
	s_waitcnt lgkmcnt(1)
	v_mfma_f32_32x32x16_bf16 v[48:63], v[122:125], v[170:173], v[48:63]
	s_waitcnt lgkmcnt(0)
	v_mfma_f32_32x32x16_bf16 v[32:47], v[122:125], v[174:177], v[32:47]
	v_mfma_f32_32x32x16_bf16 v[16:31], v[126:129], v[170:173], v[16:31]
	v_mfma_f32_32x32x16_bf16 v[0:15], v[126:129], v[174:177], v[0:15]
	ds_read_b128 v[122:125], v242 offset:96
	ds_read_b128 v[126:129], v242 offset:4704
	ds_read_b128 v[170:173], v238 offset:36960
	ds_read_b128 v[174:177], v238 offset:41568
	s_waitcnt vmcnt(11)
	ds_write_b128 v219, v[64:67] offset:55296
	s_waitcnt vmcnt(7)
	ds_write_b128 v221, v[72:75] offset:55296
	ds_write_b128 v223, v[68:71] offset:55296
	ds_write_b128 v225, v[76:79] offset:55296
	v_add_u32_e32 v64, v216, v213
	ds_write_b128 v64, v[82:85]
	v_add_u32_e32 v64, v216, v215
	s_waitcnt vmcnt(6)
	ds_write_b128 v64, v[86:89]
	s_waitcnt lgkmcnt(0)
	s_barrier
	v_lshl_add_u64 v[64:65], s[28:29], 0, v[130:131]
	v_lshl_add_u64 v[68:69], s[28:29], 0, v[132:133]
	global_load_dwordx4 v[64:67], v[64:65], off offset:384
	v_lshl_add_u64 v[76:77], s[28:29], 0, v[136:137]
	global_load_dwordx4 v[72:75], v[68:69], off offset:384
	v_lshl_add_u64 v[68:69], s[28:29], 0, v[134:135]
	s_add_u32 s28, s12, s5
	s_addc_u32 s29, s13, 0
	v_lshl_add_u64 v[82:83], s[28:29], 0, v[130:131]
	v_lshl_add_u64 v[86:87], s[28:29], 0, v[132:133]
	global_load_dwordx4 v[68:71], v[68:69], off offset:384
	s_cmp_lt_u32 s27, 15
	global_load_dwordx4 v[76:79], v[76:77], off offset:384
	s_waitcnt lgkmcnt(7)
	v_mfma_f32_32x32x16_bf16 v[48:63], v[122:125], v[170:173], v[48:63]
	global_load_dwordx4 v[82:85], v[82:83], off offset:384
	s_cselect_b64 s[28:29], -1, 0
	global_load_dwordx4 v[86:89], v[86:87], off offset:384
	s_lshr_b32 s5, 0x4044, s27
	s_bitcmp1_b32 s5, 0
	s_cselect_b64 s[30:31], -1, 0
	s_and_b64 s[28:29], s[28:29], s[30:31]
	s_waitcnt lgkmcnt(6)
	v_mfma_f32_32x32x16_bf16 v[32:47], v[122:125], v[174:177], v[32:47]
	s_cmp_eq_u32 s4, 4
	s_movk_i32 s5, 0x800
	s_cselect_b32 s5, 0x400, s5
	s_cmp_lg_u32 s4, 0
	s_cselect_b32 s30, s5, 0
	v_cndmask_b32_e64 v122, 0, 1, s[28:29]
	v_cmp_ne_u32_e64 s[4:5], 1, v122
	v_mfma_f32_32x32x16_bf16 v[16:31], v[126:129], v[170:173], v[16:31]
	s_andn2_b64 vcc, exec, s[28:29]
	v_or_b32_e32 v122, s30, v231
	v_mfma_f32_32x32x16_bf16 v[0:15], v[126:129], v[174:177], v[0:15]
	s_cbranch_vccnz .LBB0_1094
	v_or_b32_e32 v90, 32, v229
	v_add_u32_e32 v94, v90, v122
	v_add_u32_e32 v90, v122, v229
	v_add_u32_e32 v180, 0x18000, v90
	v_add_u32_e32 v184, 0x18000, v94
	global_load_dwordx4 v[90:93], v90, s[6:7]
	s_nop 0
	global_load_dwordx4 v[94:97], v94, s[6:7]
	s_nop 0
	global_load_dwordx4 v[180:183], v180, s[6:7]
	s_nop 0
	global_load_dwordx4 v[184:187], v184, s[6:7]
; __device__ __forceinline__ void branch_tile(LAS unsigned char* lds, const bf16_t* omix, const bf16_t* wbr, const bf16_t* brg, bf16_t* mix, int pm, int pn, int tid) {
;     ...
;         FG_COMPUTE(1);
;         if (segend) {
;             FG_GATE(g0, 0, 0); FG_GLD(g0, 1, 0); FG_ACC(0, 0);
.LBB0_1094:
	ds_read_b128 v[124:127], v242 offset:55296
	ds_read_b128 v[170:173], v239
	ds_read_b128 v[174:177], v239 offset:4608
	s_and_b64 vcc, exec, s[4:5]
	s_waitcnt lgkmcnt(1)
	v_mfma_f32_32x32x16_bf16 v[48:63], v[124:127], v[170:173], v[48:63]
	s_waitcnt lgkmcnt(0)
	v_mfma_f32_32x32x16_bf16 v[32:47], v[124:127], v[174:177], v[32:47]
	ds_read_b128 v[124:127], v242 offset:59904
	s_waitcnt lgkmcnt(0)
	v_mfma_f32_32x32x16_bf16 v[16:31], v[124:127], v[170:173], v[16:31]
	v_mfma_f32_32x32x16_bf16 v[0:15], v[124:127], v[174:177], v[0:15]
	ds_read_b128 v[124:127], v242 offset:55328
	ds_read_b128 v[170:173], v239 offset:32
	ds_read_b128 v[174:177], v239 offset:4640
	s_waitcnt lgkmcnt(1)
	v_mfma_f32_32x32x16_bf16 v[48:63], v[124:127], v[170:173], v[48:63]
	s_waitcnt lgkmcnt(0)
	v_mfma_f32_32x32x16_bf16 v[32:47], v[124:127], v[174:177], v[32:47]
	ds_read_b128 v[124:127], v242 offset:59936
	s_waitcnt lgkmcnt(0)
	v_mfma_f32_32x32x16_bf16 v[16:31], v[124:127], v[170:173], v[16:31]
	v_mfma_f32_32x32x16_bf16 v[0:15], v[124:127], v[174:177], v[0:15]
	ds_read_b128 v[124:127], v242 offset:55360
	ds_read_b128 v[170:173], v239 offset:64
	ds_read_b128 v[174:177], v239 offset:4672
	s_waitcnt lgkmcnt(1)
	v_mfma_f32_32x32x16_bf16 v[48:63], v[124:127], v[170:173], v[48:63]
	s_waitcnt lgkmcnt(0)
	v_mfma_f32_32x32x16_bf16 v[32:47], v[124:127], v[174:177], v[32:47]
	ds_read_b128 v[124:127], v242 offset:59968
	s_waitcnt lgkmcnt(0)
	v_mfma_f32_32x32x16_bf16 v[16:31], v[124:127], v[170:173], v[16:31]
	v_mfma_f32_32x32x16_bf16 v[0:15], v[124:127], v[174:177], v[0:15]
	ds_read_b128 v[124:127], v242 offset:55392
	ds_read_b128 v[170:173], v239 offset:96
	ds_read_b128 v[174:177], v239 offset:4704
	s_waitcnt lgkmcnt(1)
	v_mfma_f32_32x32x16_bf16 v[48:63], v[124:127], v[170:173], v[48:63]
	s_waitcnt lgkmcnt(0)
	v_mfma_f32_32x32x16_bf16 v[32:47], v[124:127], v[174:177], v[32:47]
	ds_read_b128 v[124:127], v242 offset:60000
	s_waitcnt lgkmcnt(0)
	v_mfma_f32_32x32x16_bf16 v[16:31], v[124:127], v[170:173], v[16:31]
	v_mfma_f32_32x32x16_bf16 v[0:15], v[124:127], v[174:177], v[0:15]
	s_cbranch_vccnz .LBB0_1091
	s_waitcnt vmcnt(3)
	ds_write_b128 v240, v[90:93]
	ds_read_u8 v123, v241
	ds_read_u8 v124, v241 offset:48
	ds_read_u8 v125, v241 offset:96
	ds_read_u8 v126, v241 offset:144
	ds_read_u8 v127, v241 offset:384
	ds_read_u8 v128, v241 offset:432
	ds_read_u8 v129, v241 offset:480
	ds_read_u8 v170, v241 offset:528
	s_waitcnt lgkmcnt(7)
	v_cvt_f32_ubyte0_e32 v123, v123
	v_mul_f32_e32 v123, 0x3b808081, v123
	s_waitcnt lgkmcnt(6)
	v_cvt_f32_ubyte0_e32 v124, v124
	v_lshlrev_b32_e32 v179, 16, v230
	v_mul_f32_e32 v124, 0x3b808081, v124
	v_fmac_f32_e32 v179, v123, v48
	v_and_b32_e32 v48, 0xffff0000, v230
	s_waitcnt lgkmcnt(5)
	v_cvt_f32_ubyte0_e32 v125, v125
	s_waitcnt lgkmcnt(4)
	v_cvt_f32_ubyte0_e32 v126, v126
	v_fmac_f32_e32 v48, v124, v49
	v_mul_f32_e32 v125, 0x3b808081, v125
	v_mul_f32_e32 v126, 0x3b808081, v126
	v_cvt_pk_bf16_f32 v230, v179, v48
	v_lshlrev_b32_e32 v48, 16, v237
	v_and_b32_e32 v49, 0xffff0000, v237
	s_waitcnt lgkmcnt(3)
	v_cvt_f32_ubyte0_e32 v127, v127
	s_waitcnt lgkmcnt(2)
	v_cvt_f32_ubyte0_e32 v128, v128
	v_fmac_f32_e32 v48, v125, v50
	v_fmac_f32_e32 v49, v126, v51
	v_mul_f32_e32 v127, 0x3b808081, v127
	v_mul_f32_e32 v128, 0x3b808081, v128
	v_cvt_pk_bf16_f32 v237, v48, v49
	v_lshlrev_b32_e32 v48, 16, v236
	v_and_b32_e32 v49, 0xffff0000, v236
	s_waitcnt lgkmcnt(1)
	v_cvt_f32_ubyte0_e32 v129, v129
	s_waitcnt lgkmcnt(0)
	v_cvt_f32_ubyte0_e32 v170, v170
	v_fmac_f32_e32 v48, v127, v52
	v_fmac_f32_e32 v49, v128, v53
	v_mul_f32_e32 v129, 0x3b808081, v129
	v_mul_f32_e32 v170, 0x3b808081, v170
	ds_read_u8 v171, v241 offset:768
	ds_read_u8 v172, v241 offset:816
	ds_read_u8 v173, v241 offset:864
	ds_read_u8 v174, v241 offset:912
	ds_read_u8 v175, v241 offset:1152
	ds_read_u8 v176, v241 offset:1200
	ds_read_u8 v177, v241 offset:1248
	ds_read_u8 v178, v241 offset:1296
	v_cvt_pk_bf16_f32 v236, v48, v49
	v_lshlrev_b32_e32 v48, 16, v235
	v_and_b32_e32 v49, 0xffff0000, v235
	s_waitcnt lgkmcnt(7)
	v_cvt_f32_ubyte0_e32 v171, v171
	s_waitcnt lgkmcnt(6)
	v_cvt_f32_ubyte0_e32 v172, v172
	v_fmac_f32_e32 v48, v129, v54
	v_fmac_f32_e32 v49, v170, v55
	v_mul_f32_e32 v171, 0x3b808081, v171
	v_mul_f32_e32 v172, 0x3b808081, v172
	v_cvt_pk_bf16_f32 v235, v48, v49
	v_lshlrev_b32_e32 v48, 16, v234
	v_and_b32_e32 v49, 0xffff0000, v234
	s_waitcnt lgkmcnt(5)
	v_cvt_f32_ubyte0_e32 v173, v173
	s_waitcnt lgkmcnt(4)
	v_cvt_f32_ubyte0_e32 v174, v174
	v_fmac_f32_e32 v48, v171, v56
	v_fmac_f32_e32 v49, v172, v57
	v_mul_f32_e32 v173, 0x3b808081, v173
	v_mul_f32_e32 v174, 0x3b808081, v174
	v_cvt_pk_bf16_f32 v234, v48, v49
	v_lshlrev_b32_e32 v48, 16, v233
	v_and_b32_e32 v49, 0xffff0000, v233
	s_waitcnt lgkmcnt(3)
	v_cvt_f32_ubyte0_e32 v175, v175
	s_waitcnt lgkmcnt(2)
	v_cvt_f32_ubyte0_e32 v176, v176
	v_fmac_f32_e32 v48, v173, v58
	v_fmac_f32_e32 v49, v174, v59
	v_mul_f32_e32 v175, 0x3b808081, v175
	v_mul_f32_e32 v176, 0x3b808081, v176
	v_cvt_pk_bf16_f32 v233, v48, v49
	v_lshlrev_b32_e32 v48, 16, v232
	v_and_b32_e32 v49, 0xffff0000, v232
	s_waitcnt lgkmcnt(1)
	v_cvt_f32_ubyte0_e32 v177, v177
	s_waitcnt lgkmcnt(0)
	v_cvt_f32_ubyte0_e32 v178, v178
	v_fmac_f32_e32 v48, v175, v60
	v_fmac_f32_e32 v49, v176, v61
	v_mul_f32_e32 v177, 0x3b808081, v177
	v_mul_f32_e32 v178, 0x3b808081, v178
	v_cvt_pk_bf16_f32 v232, v48, v49
	v_lshlrev_b32_e32 v48, 16, v80
	v_and_b32_e32 v49, 0xffff0000, v80
	v_fmac_f32_e32 v48, v177, v62
	v_fmac_f32_e32 v49, v178, v63
	v_cvt_pk_bf16_f32 v80, v48, v49
	s_waitcnt vmcnt(2)
; __device__ __forceinline__ void branch_tile(LAS unsigned char* lds, const bf16_t* omix, const bf16_t* wbr, const bf16_t* brg, bf16_t* mix, int pm, int pn, int tid) {
;     ...
;             FG_GATE(g1, 0, 1); FG_GLD(g1, 1, 1); FG_ACC(0, 1);
;             FG_GATE(g0, 1, 0); FG_ACC(1, 0);
;             FG_GATE(g1, 1, 1); FG_ACC(1, 1);
	ds_write_b128 v240, v[94:97]
	ds_read_u8 v48, v241
	ds_read_u8 v49, v241 offset:48
	ds_read_u8 v50, v241 offset:96
	ds_read_u8 v51, v241 offset:144
	ds_read_u8 v52, v241 offset:384
	ds_read_u8 v53, v241 offset:432
	ds_read_u8 v54, v241 offset:480
	ds_read_u8 v55, v241 offset:528
	s_waitcnt lgkmcnt(7)
	v_cvt_f32_ubyte0_e32 v48, v48
	v_mul_f32_e32 v48, 0x3b808081, v48
	s_waitcnt lgkmcnt(6)
	v_cvt_f32_ubyte0_e32 v49, v49
	v_lshlrev_b32_e32 v122, 16, v228
	v_mul_f32_e32 v49, 0x3b808081, v49
	v_fmac_f32_e32 v122, v48, v32
	v_and_b32_e32 v32, 0xffff0000, v228
	s_waitcnt lgkmcnt(5)
	v_cvt_f32_ubyte0_e32 v50, v50
	s_waitcnt lgkmcnt(4)
	v_cvt_f32_ubyte0_e32 v51, v51
	v_fmac_f32_e32 v32, v49, v33
	v_mul_f32_e32 v50, 0x3b808081, v50
	v_mul_f32_e32 v51, 0x3b808081, v51
	v_cvt_pk_bf16_f32 v228, v122, v32
	v_lshlrev_b32_e32 v32, 16, v227
	v_and_b32_e32 v33, 0xffff0000, v227
	s_waitcnt lgkmcnt(3)
	v_cvt_f32_ubyte0_e32 v52, v52
	s_waitcnt lgkmcnt(2)
	v_cvt_f32_ubyte0_e32 v53, v53
	v_fmac_f32_e32 v32, v50, v34
	v_fmac_f32_e32 v33, v51, v35
	v_mul_f32_e32 v52, 0x3b808081, v52
	v_mul_f32_e32 v53, 0x3b808081, v53
	v_cvt_pk_bf16_f32 v227, v32, v33
	v_lshlrev_b32_e32 v32, 16, v226
	v_and_b32_e32 v33, 0xffff0000, v226
	s_waitcnt lgkmcnt(1)
	v_cvt_f32_ubyte0_e32 v54, v54
	s_waitcnt lgkmcnt(0)
	v_cvt_f32_ubyte0_e32 v55, v55
	v_fmac_f32_e32 v32, v52, v36
	v_fmac_f32_e32 v33, v53, v37
	v_mul_f32_e32 v54, 0x3b808081, v54
	v_mul_f32_e32 v55, 0x3b808081, v55
	ds_read_u8 v56, v241 offset:768
	ds_read_u8 v57, v241 offset:816
	ds_read_u8 v58, v241 offset:864
	ds_read_u8 v59, v241 offset:912
	ds_read_u8 v60, v241 offset:1152
	ds_read_u8 v61, v241 offset:1200
	ds_read_u8 v62, v241 offset:1248
	ds_read_u8 v63, v241 offset:1296
	v_cvt_pk_bf16_f32 v226, v32, v33
	v_lshlrev_b32_e32 v32, 16, v224
	v_and_b32_e32 v33, 0xffff0000, v224
	s_waitcnt lgkmcnt(7)
	v_cvt_f32_ubyte0_e32 v56, v56
	s_waitcnt lgkmcnt(6)
	v_cvt_f32_ubyte0_e32 v57, v57
	v_fmac_f32_e32 v32, v54, v38
	v_fmac_f32_e32 v33, v55, v39
	v_mul_f32_e32 v56, 0x3b808081, v56
	v_mul_f32_e32 v57, 0x3b808081, v57
	v_cvt_pk_bf16_f32 v224, v32, v33
	v_lshlrev_b32_e32 v32, 16, v222
	v_and_b32_e32 v33, 0xffff0000, v222
	s_waitcnt lgkmcnt(5)
	v_cvt_f32_ubyte0_e32 v58, v58
	s_waitcnt lgkmcnt(4)
	v_cvt_f32_ubyte0_e32 v59, v59
	v_fmac_f32_e32 v32, v56, v40
	v_fmac_f32_e32 v33, v57, v41
	v_mul_f32_e32 v58, 0x3b808081, v58
	v_mul_f32_e32 v59, 0x3b808081, v59
	v_cvt_pk_bf16_f32 v222, v32, v33
	v_lshlrev_b32_e32 v32, 16, v220
	v_and_b32_e32 v33, 0xffff0000, v220
	s_waitcnt lgkmcnt(3)
	v_cvt_f32_ubyte0_e32 v60, v60
	s_waitcnt lgkmcnt(2)
	v_cvt_f32_ubyte0_e32 v61, v61
	v_fmac_f32_e32 v32, v58, v42
	v_fmac_f32_e32 v33, v59, v43
	v_mul_f32_e32 v60, 0x3b808081, v60
	v_mul_f32_e32 v61, 0x3b808081, v61
	v_cvt_pk_bf16_f32 v220, v32, v33
	v_lshlrev_b32_e32 v32, 16, v218
	v_and_b32_e32 v33, 0xffff0000, v218
	s_waitcnt lgkmcnt(1)
	v_cvt_f32_ubyte0_e32 v62, v62
	s_waitcnt lgkmcnt(0)
	v_cvt_f32_ubyte0_e32 v63, v63
	v_fmac_f32_e32 v32, v60, v44
	v_fmac_f32_e32 v33, v61, v45
	v_mul_f32_e32 v62, 0x3b808081, v62
	v_mul_f32_e32 v63, 0x3b808081, v63
	v_cvt_pk_bf16_f32 v218, v32, v33
	v_lshlrev_b32_e32 v32, 16, v217
	v_and_b32_e32 v33, 0xffff0000, v217
	v_fmac_f32_e32 v32, v62, v46
	v_fmac_f32_e32 v33, v63, v47
	s_waitcnt vmcnt(1)
	ds_write_b128 v240, v[180:183]
	v_cvt_pk_bf16_f32 v217, v32, v33
	ds_read_u8 v32, v241
	ds_read_u8 v33, v241 offset:48
	ds_read_u8 v34, v241 offset:96
	ds_read_u8 v35, v241 offset:144
	ds_read_u8 v36, v241 offset:384
	ds_read_u8 v37, v241 offset:432
	ds_read_u8 v38, v241 offset:480
	ds_read_u8 v39, v241 offset:528
	s_waitcnt lgkmcnt(7)
	v_cvt_f32_ubyte0_e32 v32, v32
	v_mul_f32_e32 v32, 0x3b808081, v32
	s_waitcnt lgkmcnt(6)
	v_cvt_f32_ubyte0_e32 v33, v33
	v_lshlrev_b32_e32 v48, 16, v210
	v_mul_f32_e32 v33, 0x3b808081, v33
	v_fmac_f32_e32 v48, v32, v16
	v_and_b32_e32 v16, 0xffff0000, v210
	s_waitcnt lgkmcnt(5)
	v_cvt_f32_ubyte0_e32 v34, v34
	s_waitcnt lgkmcnt(4)
	v_cvt_f32_ubyte0_e32 v35, v35
	v_fmac_f32_e32 v16, v33, v17
	v_mul_f32_e32 v34, 0x3b808081, v34
	v_mul_f32_e32 v35, 0x3b808081, v35
	v_cvt_pk_bf16_f32 v210, v48, v16
	v_lshlrev_b32_e32 v16, 16, v163
	v_and_b32_e32 v17, 0xffff0000, v163
	s_waitcnt lgkmcnt(3)
	v_cvt_f32_ubyte0_e32 v36, v36
	s_waitcnt lgkmcnt(2)
	v_cvt_f32_ubyte0_e32 v37, v37
	v_fmac_f32_e32 v16, v34, v18
	v_fmac_f32_e32 v17, v35, v19
	v_mul_f32_e32 v36, 0x3b808081, v36
	v_mul_f32_e32 v37, 0x3b808081, v37
	v_cvt_pk_bf16_f32 v163, v16, v17
	v_lshlrev_b32_e32 v16, 16, v162
	v_and_b32_e32 v17, 0xffff0000, v162
	s_waitcnt lgkmcnt(1)
	v_cvt_f32_ubyte0_e32 v38, v38
	s_waitcnt lgkmcnt(0)
	v_cvt_f32_ubyte0_e32 v39, v39
	v_fmac_f32_e32 v16, v36, v20
	v_fmac_f32_e32 v17, v37, v21
	v_mul_f32_e32 v38, 0x3b808081, v38
	v_mul_f32_e32 v39, 0x3b808081, v39
	ds_read_u8 v40, v241 offset:768
	ds_read_u8 v41, v241 offset:816
	ds_read_u8 v42, v241 offset:864
	ds_read_u8 v43, v241 offset:912
	ds_read_u8 v44, v241 offset:1152
	ds_read_u8 v45, v241 offset:1200
	ds_read_u8 v46, v241 offset:1248
	ds_read_u8 v47, v241 offset:1296
	v_cvt_pk_bf16_f32 v162, v16, v17
	v_lshlrev_b32_e32 v16, 16, v160
	v_and_b32_e32 v17, 0xffff0000, v160
	s_waitcnt lgkmcnt(7)
	v_cvt_f32_ubyte0_e32 v40, v40
	s_waitcnt lgkmcnt(6)
	v_cvt_f32_ubyte0_e32 v41, v41
	v_fmac_f32_e32 v16, v38, v22
	v_fmac_f32_e32 v17, v39, v23
	v_mul_f32_e32 v40, 0x3b808081, v40
	v_mul_f32_e32 v41, 0x3b808081, v41
	v_cvt_pk_bf16_f32 v160, v16, v17
	v_lshlrev_b32_e32 v16, 16, v158
	v_and_b32_e32 v17, 0xffff0000, v158
	s_waitcnt lgkmcnt(5)
	v_cvt_f32_ubyte0_e32 v42, v42
	s_waitcnt lgkmcnt(4)
; __device__ __forceinline__ void branch_tile(LAS unsigned char* lds, const bf16_t* omix, const bf16_t* wbr, const bf16_t* brg, bf16_t* mix, int pm, int pn, int tid) {
;     ...
;             FG_GATE(g1, 1, 1); FG_ACC(1, 1);
	v_cvt_f32_ubyte0_e32 v43, v43
	v_fmac_f32_e32 v16, v40, v24
	v_fmac_f32_e32 v17, v41, v25
	v_mul_f32_e32 v42, 0x3b808081, v42
	v_mul_f32_e32 v43, 0x3b808081, v43
	v_cvt_pk_bf16_f32 v158, v16, v17
	v_lshlrev_b32_e32 v16, 16, v157
	v_and_b32_e32 v17, 0xffff0000, v157
	s_waitcnt lgkmcnt(3)
	v_cvt_f32_ubyte0_e32 v44, v44
	s_waitcnt lgkmcnt(2)
	v_cvt_f32_ubyte0_e32 v45, v45
	v_fmac_f32_e32 v16, v42, v26
	v_fmac_f32_e32 v17, v43, v27
	v_mul_f32_e32 v44, 0x3b808081, v44
	v_mul_f32_e32 v45, 0x3b808081, v45
	v_cvt_pk_bf16_f32 v157, v16, v17
	v_lshlrev_b32_e32 v16, 16, v156
	v_and_b32_e32 v17, 0xffff0000, v156
	s_waitcnt lgkmcnt(1)
	v_cvt_f32_ubyte0_e32 v46, v46
	s_waitcnt lgkmcnt(0)
	v_cvt_f32_ubyte0_e32 v47, v47
	v_fmac_f32_e32 v16, v44, v28
	v_fmac_f32_e32 v17, v45, v29
	v_mul_f32_e32 v46, 0x3b808081, v46
	v_mul_f32_e32 v47, 0x3b808081, v47
	v_cvt_pk_bf16_f32 v156, v16, v17
	v_lshlrev_b32_e32 v16, 16, v155
	v_and_b32_e32 v17, 0xffff0000, v155
	v_fmac_f32_e32 v16, v46, v30
	v_fmac_f32_e32 v17, v47, v31
	s_waitcnt vmcnt(0)
	ds_write_b128 v240, v[184:187]
	v_cvt_pk_bf16_f32 v155, v16, v17
	ds_read_u8 v16, v241
	ds_read_u8 v17, v241 offset:48
	ds_read_u8 v18, v241 offset:96
	ds_read_u8 v19, v241 offset:144
	ds_read_u8 v20, v241 offset:384
	ds_read_u8 v21, v241 offset:432
	ds_read_u8 v22, v241 offset:480
	ds_read_u8 v23, v241 offset:528
	s_waitcnt lgkmcnt(7)
	v_cvt_f32_ubyte0_e32 v16, v16
	v_mul_f32_e32 v16, 0x3b808081, v16
	s_waitcnt lgkmcnt(6)
	v_cvt_f32_ubyte0_e32 v17, v17
	v_lshlrev_b32_e32 v32, 16, v154
	v_mul_f32_e32 v17, 0x3b808081, v17
	v_fmac_f32_e32 v32, v16, v0
	v_and_b32_e32 v0, 0xffff0000, v154
	s_waitcnt lgkmcnt(5)
	v_cvt_f32_ubyte0_e32 v18, v18
	s_waitcnt lgkmcnt(4)
	v_cvt_f32_ubyte0_e32 v19, v19
	v_fmac_f32_e32 v0, v17, v1
	v_mul_f32_e32 v18, 0x3b808081, v18
	v_mul_f32_e32 v19, 0x3b808081, v19
	v_cvt_pk_bf16_f32 v154, v32, v0
	v_lshlrev_b32_e32 v0, 16, v153
	v_and_b32_e32 v1, 0xffff0000, v153
	s_waitcnt lgkmcnt(3)
	v_cvt_f32_ubyte0_e32 v20, v20
	s_waitcnt lgkmcnt(2)
	v_cvt_f32_ubyte0_e32 v21, v21
	v_fmac_f32_e32 v0, v18, v2
	v_fmac_f32_e32 v1, v19, v3
	v_mul_f32_e32 v20, 0x3b808081, v20
	v_mul_f32_e32 v21, 0x3b808081, v21
	v_cvt_pk_bf16_f32 v153, v0, v1
	v_lshlrev_b32_e32 v0, 16, v152
	v_and_b32_e32 v1, 0xffff0000, v152
	s_waitcnt lgkmcnt(1)
	v_cvt_f32_ubyte0_e32 v22, v22
	s_waitcnt lgkmcnt(0)
	v_cvt_f32_ubyte0_e32 v23, v23
	v_fmac_f32_e32 v0, v20, v4
	v_fmac_f32_e32 v1, v21, v5
	v_mul_f32_e32 v22, 0x3b808081, v22
	v_mul_f32_e32 v23, 0x3b808081, v23
	ds_read_u8 v24, v241 offset:768
	ds_read_u8 v25, v241 offset:816
	ds_read_u8 v26, v241 offset:864
	ds_read_u8 v27, v241 offset:912
	ds_read_u8 v28, v241 offset:1152
	ds_read_u8 v29, v241 offset:1200
	ds_read_u8 v30, v241 offset:1248
	ds_read_u8 v31, v241 offset:1296
	v_cvt_pk_bf16_f32 v152, v0, v1
	v_lshlrev_b32_e32 v0, 16, v145
	v_and_b32_e32 v1, 0xffff0000, v145
	s_waitcnt lgkmcnt(7)
	v_cvt_f32_ubyte0_e32 v24, v24
	s_waitcnt lgkmcnt(6)
	v_cvt_f32_ubyte0_e32 v25, v25
	v_fmac_f32_e32 v0, v22, v6
	v_fmac_f32_e32 v1, v23, v7
	v_mul_f32_e32 v24, 0x3b808081, v24
	v_mul_f32_e32 v25, 0x3b808081, v25
	v_cvt_pk_bf16_f32 v145, v0, v1
	v_lshlrev_b32_e32 v0, 16, v144
	v_and_b32_e32 v1, 0xffff0000, v144
	s_waitcnt lgkmcnt(5)
	v_cvt_f32_ubyte0_e32 v26, v26
	s_waitcnt lgkmcnt(4)
	v_cvt_f32_ubyte0_e32 v27, v27
	v_fmac_f32_e32 v0, v24, v8
	v_fmac_f32_e32 v1, v25, v9
	v_mul_f32_e32 v26, 0x3b808081, v26
	v_mul_f32_e32 v27, 0x3b808081, v27
	v_cvt_pk_bf16_f32 v144, v0, v1
	v_lshlrev_b32_e32 v0, 16, v143
	v_and_b32_e32 v1, 0xffff0000, v143
	s_waitcnt lgkmcnt(3)
	v_cvt_f32_ubyte0_e32 v28, v28
	s_waitcnt lgkmcnt(2)
	v_cvt_f32_ubyte0_e32 v29, v29
	v_fmac_f32_e32 v0, v26, v10
	v_fmac_f32_e32 v1, v27, v11
	v_mul_f32_e32 v28, 0x3b808081, v28
	v_mul_f32_e32 v29, 0x3b808081, v29
	v_cvt_pk_bf16_f32 v143, v0, v1
	v_lshlrev_b32_e32 v0, 16, v142
	v_and_b32_e32 v1, 0xffff0000, v142
	s_waitcnt lgkmcnt(1)
	v_cvt_f32_ubyte0_e32 v30, v30
	s_waitcnt lgkmcnt(0)
	v_cvt_f32_ubyte0_e32 v31, v31
	v_fmac_f32_e32 v0, v28, v12
	v_fmac_f32_e32 v1, v29, v13
	v_mul_f32_e32 v30, 0x3b808081, v30
	v_mul_f32_e32 v31, 0x3b808081, v31
	v_cvt_pk_bf16_f32 v142, v0, v1
	v_lshlrev_b32_e32 v0, 16, v141
	v_and_b32_e32 v1, 0xffff0000, v141
	v_fmac_f32_e32 v0, v30, v14
	v_fmac_f32_e32 v1, v31, v15
	v_cvt_pk_bf16_f32 v141, v0, v1
	v_mov_b32_e32 v0, 0
	v_mov_b32_e32 v1, v0
	v_mov_b32_e32 v2, v0
	v_mov_b32_e32 v3, v0
	v_mov_b32_e32 v4, v0
	v_mov_b32_e32 v5, v0
	v_mov_b32_e32 v6, v0
	v_mov_b32_e32 v7, v0
	v_mov_b32_e32 v8, v0
	v_mov_b32_e32 v9, v0
	v_mov_b32_e32 v10, v0
	v_mov_b32_e32 v11, v0
	v_mov_b32_e32 v12, v0
	v_mov_b32_e32 v13, v0
	v_mov_b32_e32 v14, v0
	v_mov_b32_e32 v15, v0
	v_mov_b32_e32 v16, v0
	v_mov_b32_e32 v17, v0
	v_mov_b32_e32 v18, v0
	v_mov_b32_e32 v19, v0
	v_mov_b32_e32 v20, v0
	v_mov_b32_e32 v21, v0
	v_mov_b32_e32 v22, v0
	v_mov_b32_e32 v23, v0
	v_mov_b32_e32 v24, v0
	v_mov_b32_e32 v25, v0
	v_mov_b32_e32 v26, v0
	v_mov_b32_e32 v27, v0
	v_mov_b32_e32 v28, v0
	v_mov_b32_e32 v29, v0
	v_mov_b32_e32 v30, v0
	v_mov_b32_e32 v31, v0
	v_mov_b32_e32 v32, v0
	v_mov_b32_e32 v33, v0
	v_mov_b32_e32 v34, v0
	v_mov_b32_e32 v35, v0
	v_mov_b32_e32 v36, v0
	v_mov_b32_e32 v37, v0
	v_mov_b32_e32 v38, v0
	v_mov_b32_e32 v39, v0
	v_mov_b32_e32 v40, v0
	v_mov_b32_e32 v41, v0
	v_mov_b32_e32 v42, v0
	v_mov_b32_e32 v43, v0
	v_mov_b32_e32 v44, v0
	v_mov_b32_e32 v45, v0
	v_mov_b32_e32 v46, v0
	v_mov_b32_e32 v47, v0
	v_mov_b32_e32 v48, v0
	v_mov_b32_e32 v49, v0
	v_mov_b32_e32 v50, v0
	v_mov_b32_e32 v51, v0
	v_mov_b32_e32 v52, v0
	v_mov_b32_e32 v53, v0
	v_mov_b32_e32 v54, v0
	v_mov_b32_e32 v55, v0
	v_mov_b32_e32 v56, v0
	v_mov_b32_e32 v57, v0
	v_mov_b32_e32 v58, v0
	v_mov_b32_e32 v59, v0
	v_mov_b32_e32 v60, v0
	v_mov_b32_e32 v61, v0
	v_mov_b32_e32 v62, v0
	v_mov_b32_e32 v63, v0
	s_branch .LBB0_1091
